# code placement: the three GEMM K-loop heads aligned to 64 bytes
# speedup vs baseline: 1.0013x; 1.0013x over previous
;     DI bool next(int i, pg8::Unit& u) const { const int id = c + i * G; if (id >= 160) return false; const int t = id >> 1; u.pm = 64 + t / 40; u.pn = ctx_pn(t % 40); u.z = id & 1; return true; }
;     DI bool next(int i, pg8::Unit& u) const { if (i >= 4) return false; u.z = 0; u.pm = 16 * i + 4 * (x & 3) + (s & 3); u.pn = 8 * (x >> 2) + (s >> 2); return true; }
; template <class Epi, class Sched>
; DI void gemm_phase(LAS unsigned char* lds, const Gemm g, const Sched& S, const Epi& E) {
;     ...
;         const bool has_next = S.next(ui + 1, nxt);
;         const char* nA = has_next ? PG8_ABASE(nxt) : cA; const char* nB = has_next ? PG8_BBASE(nxt) : cB;
;         for (int t = 0; t < nt; t += 2) {
;             const bool last = (t == nt - 2);
;             const char* a1 = cA + (size_t)(t + 1) * kstep;
;             const char* a2 = last ? nA : cA + (size_t)(t + 2) * kstep; const char* b2 = last ? nB : cB + (size_t)(t + 2) * kstep;
;             const char* a3 = a2 + kstep; const char* b3 = b2 + kstep;
;     ...
; #pragma unroll
;         for (int a = 0; a < 2; ++a)
; #pragma unroll
;             for (int b = 0; b < 2; ++b)
; #pragma unroll
;                 for (int m = 0; m < 4; ++m)
; #pragma unroll
;                     for (int n = 0; n < 2; ++n) acc[a][b][m][n] = (f32x4){0.f, 0.f, 0.f, 0.f};
.LBB0_175:
	s_ashr_i32 s17, s16, 31
	v_cmp_lt_i64_e32 vcc, s[18:19], v[142:143]
	s_lshl_b64 s[18:19], s[16:17], 21
	s_add_u32 s18, s8, s18
	s_addc_u32 s19, s9, s19
	s_and_b64 s[20:21], vcc, exec
	s_cselect_b32 s5, s19, s25
	s_cselect_b32 s17, s18, s24
	s_ashr_i32 s15, s14, 31
	s_lshl_b64 s[20:21], s[14:15], 21
	s_add_u32 s20, s74, s20
	s_addc_u32 s21, s75, s21
	s_and_b64 s[28:29], vcc, exec
	s_cselect_b32 s15, s21, s27
	s_cselect_b32 s23, s20, s26
	s_add_u32 s24, s24, 0x100080
	s_addc_u32 s25, s25, 0
	s_add_u32 s63, s26, 0x100
	v_mov_b32_e32 v0, 0
	s_addc_u32 s64, s27, 0
	s_mov_b32 s65, -2
	v_mov_b32_e32 v1, v0
	v_mov_b32_e32 v2, v0
	v_mov_b32_e32 v3, v0
	v_mov_b32_e32 v4, v0
	v_mov_b32_e32 v5, v0
	v_mov_b32_e32 v6, v0
	v_mov_b32_e32 v7, v0
	v_mov_b32_e32 v16, v0
	v_mov_b32_e32 v17, v0
	v_mov_b32_e32 v18, v0
	v_mov_b32_e32 v19, v0
	v_mov_b32_e32 v20, v0
	v_mov_b32_e32 v21, v0
	v_mov_b32_e32 v22, v0
	v_mov_b32_e32 v23, v0
	v_mov_b32_e32 v32, v0
	v_mov_b32_e32 v33, v0
	v_mov_b32_e32 v34, v0
	v_mov_b32_e32 v35, v0
	v_mov_b32_e32 v36, v0
	v_mov_b32_e32 v37, v0
	v_mov_b32_e32 v38, v0
	v_mov_b32_e32 v39, v0
	v_mov_b32_e32 v48, v0
	v_mov_b32_e32 v49, v0
	v_mov_b32_e32 v50, v0
	v_mov_b32_e32 v51, v0
	v_mov_b32_e32 v52, v0
	v_mov_b32_e32 v53, v0
	v_mov_b32_e32 v54, v0
	v_mov_b32_e32 v55, v0
	v_mov_b32_e32 v8, v0
	v_mov_b32_e32 v9, v0
	v_mov_b32_e32 v10, v0
	v_mov_b32_e32 v11, v0
	v_mov_b32_e32 v12, v0
	v_mov_b32_e32 v13, v0
	v_mov_b32_e32 v14, v0
	v_mov_b32_e32 v15, v0
	v_mov_b32_e32 v24, v0
	v_mov_b32_e32 v25, v0
	v_mov_b32_e32 v26, v0
	v_mov_b32_e32 v27, v0
	v_mov_b32_e32 v28, v0
	v_mov_b32_e32 v29, v0
	v_mov_b32_e32 v30, v0
	v_mov_b32_e32 v31, v0
	v_mov_b32_e32 v40, v0
	v_mov_b32_e32 v41, v0
	v_mov_b32_e32 v42, v0
	v_mov_b32_e32 v43, v0
	v_mov_b32_e32 v44, v0
	v_mov_b32_e32 v45, v0
	v_mov_b32_e32 v46, v0
	v_mov_b32_e32 v47, v0
	v_mov_b32_e32 v56, v0
	v_mov_b32_e32 v57, v0
	v_mov_b32_e32 v58, v0
	v_mov_b32_e32 v59, v0
	v_mov_b32_e32 v60, v0
	v_mov_b32_e32 v61, v0
	v_mov_b32_e32 v62, v0
	v_mov_b32_e32 v63, v0
	v_mov_b32_e32 v64, v0
	v_mov_b32_e32 v65, v0
	v_mov_b32_e32 v66, v0
	v_mov_b32_e32 v67, v0
	v_mov_b32_e32 v68, v0
	v_mov_b32_e32 v69, v0
	v_mov_b32_e32 v70, v0
	v_mov_b32_e32 v71, v0
	v_mov_b32_e32 v80, v0
	v_mov_b32_e32 v81, v0
	v_mov_b32_e32 v82, v0
	v_mov_b32_e32 v83, v0
	v_mov_b32_e32 v84, v0
	v_mov_b32_e32 v85, v0
	v_mov_b32_e32 v86, v0
	v_mov_b32_e32 v87, v0
	v_mov_b32_e32 v96, v0
	v_mov_b32_e32 v97, v0
	v_mov_b32_e32 v98, v0
	v_mov_b32_e32 v99, v0
	v_mov_b32_e32 v100, v0
	v_mov_b32_e32 v101, v0
	v_mov_b32_e32 v102, v0
	v_mov_b32_e32 v103, v0
	v_mov_b32_e32 v112, v0
	v_mov_b32_e32 v113, v0
	v_mov_b32_e32 v114, v0
	v_mov_b32_e32 v115, v0
	v_mov_b32_e32 v116, v0
	v_mov_b32_e32 v117, v0
	v_mov_b32_e32 v118, v0
	v_mov_b32_e32 v119, v0
	v_mov_b32_e32 v72, v0
	v_mov_b32_e32 v73, v0
	v_mov_b32_e32 v74, v0
	v_mov_b32_e32 v75, v0
	v_mov_b32_e32 v76, v0
	v_mov_b32_e32 v77, v0
	v_mov_b32_e32 v78, v0
	v_mov_b32_e32 v79, v0
	v_mov_b32_e32 v88, v0
	v_mov_b32_e32 v89, v0
	v_mov_b32_e32 v90, v0
	v_mov_b32_e32 v91, v0
	v_mov_b32_e32 v92, v0
	v_mov_b32_e32 v93, v0
	v_mov_b32_e32 v94, v0
	v_mov_b32_e32 v95, v0
	v_mov_b32_e32 v104, v0
	v_mov_b32_e32 v105, v0
	v_mov_b32_e32 v106, v0
	v_mov_b32_e32 v107, v0
	v_mov_b32_e32 v108, v0
	v_mov_b32_e32 v109, v0
	v_mov_b32_e32 v110, v0
	v_mov_b32_e32 v111, v0
	v_mov_b32_e32 v120, v0
	v_mov_b32_e32 v121, v0
	v_mov_b32_e32 v122, v0
	v_mov_b32_e32 v123, v0
	v_mov_b32_e32 v124, v0
	v_mov_b32_e32 v125, v0
	v_mov_b32_e32 v126, v0
	v_mov_b32_e32 v127, v0
	.p2align	6

;     DI bool next(int i, pg8::Unit& u) const { const int id = c + i * G; if (id >= 160) return false; const int t = id >> 1; u.pm = 64 + t / 40; u.pn = ctx_pn(t % 40); u.z = id & 1; return true; }
;     DI bool next(int i, pg8::Unit& u) const { if (i >= 4) return false; u.z = 0; u.pm = 16 * i + 4 * (x & 3) + (s & 3); u.pn = 8 * (x >> 2) + (s >> 2); return true; }
; template <class Epi, class Sched>
; DI void gemm_phase(LAS unsigned char* lds, const Gemm g, const Sched& S, const Epi& E) {
;     ...
;         const bool has_next = S.next(ui + 1, nxt);
;         const char* nA = has_next ? PG8_ABASE(nxt) : cA; const char* nB = has_next ? PG8_BBASE(nxt) : cB;
;         for (int t = 0; t < nt; t += 2) {
;             const bool last = (t == nt - 2);
;             const char* a1 = cA + (size_t)(t + 1) * kstep;
;             const char* a2 = last ? nA : cA + (size_t)(t + 2) * kstep; const char* b2 = last ? nB : cB + (size_t)(t + 2) * kstep;
;             const char* a3 = a2 + kstep; const char* b3 = b2 + kstep;
.LBB0_725:
	s_ashr_i32 s19, s18, 31
	s_lshl_b64 s[20:21], s[18:19], 20
	s_cmp_eq_u32 s62, 0
	s_cselect_b32 s17, s35, s48
	s_cselect_b32 s5, s36, s49
	s_cselect_b32 s28, s37, s50
	s_cselect_b32 s29, s40, s51
	s_add_u32 s20, s17, s20
	v_cmp_lt_i64_e64 s[8:9], s[8:9], v[212:213]
	s_addc_u32 s21, s5, s21
	s_and_b64 s[22:23], s[8:9], exec
	s_cselect_b32 s5, s21, s25
	s_cselect_b32 s19, s20, s24
	s_ashr_i32 s17, s16, 31
	s_lshl_b64 s[22:23], s[16:17], 20
	s_add_u32 s22, s28, s22
	s_addc_u32 s23, s29, s23
	s_and_b64 s[28:29], s[8:9], exec
	s_cselect_b32 s17, s23, s27
	s_cselect_b32 s30, s22, s26
	s_add_u32 s24, s24, 0x80080
	s_addc_u32 s25, s25, 0
	s_add_u32 s31, s26, 0x100
	s_addc_u32 s63, s27, 0
	s_mov_b32 s64, -2
	.p2align	6

; template <class Epi, class Sched>
; DI void gemm_phase(LAS unsigned char* lds, const Gemm g, const Sched& S, const Epi& E) {
;     ...
;         const bool has_next = S.next(ui + 1, nxt);
;         const char* nA = has_next ? PG8_ABASE(nxt) : cA; const char* nB = has_next ? PG8_BBASE(nxt) : cB;
;         for (int t = 0; t < nt; t += 2) {
;             const bool last = (t == nt - 2);
;             const char* a1 = cA + (size_t)(t + 1) * kstep;
;             const char* a2 = last ? nA : cA + (size_t)(t + 2) * kstep; const char* b2 = last ? nB : cB + (size_t)(t + 2) * kstep;
;             const char* a3 = a2 + kstep; const char* b3 = b2 + kstep;
;             PG8_LDB(B0, 0, 0); PG8_SCHED; PG8_LDA(At, 0, 0); PG8_STAGE(PG8_SA(1, 1), a1 + hstep, voffA);
;             PG8_WAIT_L(8); PG8_BAR; PG8_WAIT_L(0); PG8_MMA(0, 0, At, B0); PG8_BAR; PG8_SCHED;
;             PG8_LDB(B1, 0, 1); PG8_STAGE(PG8_SB(0, 0), b2, voffB);
;             PG8_BAR; PG8_WAIT_L(0); PG8_MMA(0, 1, At, B1); PG8_BAR;
;             PG8_LDA(At, 0, 1); PG8_STAGE(PG8_SA(0, 0), a2, voffA);
;             PG8_BAR; PG8_WAIT_L(0); PG8_MMA(1, 0, At, B0); PG8_BAR; PG8_SCHED;
;             PG8_STAGE(PG8_SB(0, 1), b2 + hstep, voffB);
;             PG8_WAIT_V(6); PG8_BAR; PG8_MMA(1, 1, At, B1); PG8_BAR;
;             PG8_LDB(B0, 1, 0); PG8_SCHED; PG8_LDA(At, 1, 0); PG8_STAGE(PG8_SA(0, 1), a2 + hstep, voffA);
;             PG8_WAIT_L(8); PG8_BAR; PG8_WAIT_L(0); PG8_MMA(0, 0, At, B0); PG8_BAR; PG8_SCHED;
;             PG8_LDB(B1, 1, 1); PG8_STAGE(PG8_SB(1, 0), b3, voffB);
;             PG8_BAR; PG8_WAIT_L(0); PG8_MMA(0, 1, At, B1); PG8_BAR;
;             PG8_LDA(At, 1, 1); PG8_STAGE(PG8_SA(1, 0), a3, voffA);
;             PG8_BAR; PG8_WAIT_L(0); PG8_MMA(1, 0, At, B0); PG8_BAR; PG8_SCHED;
;             PG8_STAGE(PG8_SB(1, 1), b3 + hstep, voffB);
;             PG8_WAIT_V(6); PG8_BAR; PG8_MMA(1, 1, At, B1); PG8_BAR;
;         }
;         const bool keep = E(acc, cur, wr, wc, fr, fq);
;         if (!has_next) break;
;         if (!keep) {
; #pragma unroll
;         for (int a = 0; a < 2; ++a)
; #pragma unroll
;             for (int b = 0; b < 2; ++b)
; #pragma unroll
;                 for (int m = 0; m < 4; ++m)
; #pragma unroll
;                     for (int n = 0; n < 2; ++n) acc[a][b][m][n] = (f32x4){0.f, 0.f, 0.f, 0.f};
;         }
;         cur = nxt; cA = nA; cB = nB; ++ui;
.LBB0_910:
	s_mov_b64 s[28:29], s[12:13]
	s_mov_b32 s12, s40
	s_add_i32 s40, s40, 1
	s_cmp_lt_u32 s12, 3
	s_cselect_b64 s[30:31], -1, 0
	s_lshl_b32 s12, s40, 4
	s_mov_b64 s[26:27], s[14:15]
	s_mov_b32 s14, s82
	s_or_b32 s82, s12, s34
	s_and_b64 s[12:13], s[30:31], exec
	s_cselect_b32 s14, s82, s14
	s_cselect_b32 s12, s4, s4
	s_ashr_i32 s15, s14, 31
	s_lshl_b64 s[14:15], s[14:15], 21
	s_add_u32 s14, s46, s14
	s_addc_u32 s15, s47, s15
	s_and_b64 s[84:85], s[30:31], exec
	s_cselect_b32 s25, s15, s27
	s_cselect_b32 s83, s14, s26
	s_ashr_i32 s13, s12, 31
	s_lshl_b64 s[12:13], s[12:13], 21
	s_add_u32 s12, s48, s12
	s_addc_u32 s13, s49, s13
	s_and_b64 s[30:31], s[30:31], exec
	s_cselect_b32 s84, s13, s29
	s_cselect_b32 s85, s12, s28
	s_add_u32 s26, s26, 0x100080
	s_addc_u32 s27, s27, 0
	s_add_u32 s86, s28, 0x100
	v_mov_b32_e32 v0, 0
	s_addc_u32 s87, s29, 0
	s_mov_b32 s88, -2
	v_mov_b32_e32 v1, v0
	v_mov_b32_e32 v2, v0
	v_mov_b32_e32 v3, v0
	v_mov_b32_e32 v8, v0
	v_mov_b32_e32 v9, v0
	v_mov_b32_e32 v10, v0
	v_mov_b32_e32 v11, v0
	v_mov_b32_e32 v4, v0
	v_mov_b32_e32 v5, v0
	v_mov_b32_e32 v6, v0
	v_mov_b32_e32 v7, v0
	v_mov_b32_e32 v12, v0
	v_mov_b32_e32 v13, v0
	v_mov_b32_e32 v14, v0
	v_mov_b32_e32 v15, v0
	v_mov_b32_e32 v32, v0
	v_mov_b32_e32 v33, v0
	v_mov_b32_e32 v34, v0
	v_mov_b32_e32 v35, v0
	v_mov_b32_e32 v36, v0
	v_mov_b32_e32 v37, v0
	v_mov_b32_e32 v38, v0
	v_mov_b32_e32 v39, v0
	v_mov_b32_e32 v48, v0
	v_mov_b32_e32 v49, v0
	v_mov_b32_e32 v50, v0
	v_mov_b32_e32 v51, v0
	v_mov_b32_e32 v52, v0
	v_mov_b32_e32 v53, v0
	v_mov_b32_e32 v54, v0
	v_mov_b32_e32 v55, v0
	v_mov_b32_e32 v16, v0
	v_mov_b32_e32 v17, v0
	v_mov_b32_e32 v18, v0
	v_mov_b32_e32 v19, v0
	v_mov_b32_e32 v24, v0
	v_mov_b32_e32 v25, v0
	v_mov_b32_e32 v26, v0
	v_mov_b32_e32 v27, v0
	v_mov_b32_e32 v20, v0
	v_mov_b32_e32 v21, v0
	v_mov_b32_e32 v22, v0
	v_mov_b32_e32 v23, v0
	v_mov_b32_e32 v28, v0
	v_mov_b32_e32 v29, v0
	v_mov_b32_e32 v30, v0
	v_mov_b32_e32 v31, v0
	v_mov_b32_e32 v40, v0
	v_mov_b32_e32 v41, v0
	v_mov_b32_e32 v42, v0
	v_mov_b32_e32 v43, v0
	v_mov_b32_e32 v44, v0
	v_mov_b32_e32 v45, v0
	v_mov_b32_e32 v46, v0
	v_mov_b32_e32 v47, v0
	v_mov_b32_e32 v56, v0
	v_mov_b32_e32 v57, v0
	v_mov_b32_e32 v58, v0
	v_mov_b32_e32 v59, v0
	v_mov_b32_e32 v60, v0
	v_mov_b32_e32 v61, v0
	v_mov_b32_e32 v62, v0
	v_mov_b32_e32 v63, v0
	v_mov_b32_e32 v64, v0
	v_mov_b32_e32 v65, v0
	v_mov_b32_e32 v66, v0
	v_mov_b32_e32 v67, v0
	v_mov_b32_e32 v68, v0
	v_mov_b32_e32 v69, v0
	v_mov_b32_e32 v70, v0
	v_mov_b32_e32 v71, v0
	v_mov_b32_e32 v80, v0
	v_mov_b32_e32 v81, v0
	v_mov_b32_e32 v82, v0
	v_mov_b32_e32 v83, v0
	v_mov_b32_e32 v84, v0
	v_mov_b32_e32 v85, v0
	v_mov_b32_e32 v86, v0
	v_mov_b32_e32 v87, v0
	v_mov_b32_e32 v96, v0
	v_mov_b32_e32 v97, v0
	v_mov_b32_e32 v98, v0
	v_mov_b32_e32 v99, v0
	v_mov_b32_e32 v100, v0
	v_mov_b32_e32 v101, v0
	v_mov_b32_e32 v102, v0
	v_mov_b32_e32 v103, v0
	v_mov_b32_e32 v112, v0
	v_mov_b32_e32 v113, v0
	v_mov_b32_e32 v114, v0
	v_mov_b32_e32 v115, v0
	v_mov_b32_e32 v116, v0
	v_mov_b32_e32 v117, v0
	v_mov_b32_e32 v118, v0
	v_mov_b32_e32 v119, v0
	v_mov_b32_e32 v72, v0
	v_mov_b32_e32 v73, v0
	v_mov_b32_e32 v74, v0
	v_mov_b32_e32 v75, v0
	v_mov_b32_e32 v76, v0
	v_mov_b32_e32 v77, v0
	v_mov_b32_e32 v78, v0
	v_mov_b32_e32 v79, v0
	v_mov_b32_e32 v88, v0
	v_mov_b32_e32 v89, v0
	v_mov_b32_e32 v90, v0
	v_mov_b32_e32 v91, v0
	v_mov_b32_e32 v92, v0
	v_mov_b32_e32 v93, v0
	v_mov_b32_e32 v94, v0
	v_mov_b32_e32 v95, v0
	v_mov_b32_e32 v104, v0
	v_mov_b32_e32 v105, v0
	v_mov_b32_e32 v106, v0
	v_mov_b32_e32 v107, v0
	v_mov_b32_e32 v108, v0
	v_mov_b32_e32 v109, v0
	v_mov_b32_e32 v110, v0
	v_mov_b32_e32 v111, v0
	v_mov_b32_e32 v120, v0
	v_mov_b32_e32 v121, v0
	v_mov_b32_e32 v122, v0
	v_mov_b32_e32 v123, v0
	v_mov_b32_e32 v124, v0
	v_mov_b32_e32 v125, v0
	v_mov_b32_e32 v126, v0
	v_mov_b32_e32 v127, v0
	.p2align	6
